# stack3+conv, and the XCD generation word is no longer written (leaders skip one atomic + its wait per barrier)
# speedup vs baseline: 1.0086x; 1.0012x over previous
; DEVI unsigned xb_ld(unsigned* p)              { return __hip_atomic_load(p, __ATOMIC_RELAXED, __HIP_MEMORY_SCOPE_AGENT); }
; DEVI unsigned xb_add(unsigned* p, unsigned v) { return __hip_atomic_fetch_add(p, v, __ATOMIC_RELAXED, __HIP_MEMORY_SCOPE_AGENT); }
; #define XB_SPIN(cond, bar) do { unsigned _sp = 0; while (cond) { __builtin_amdgcn_s_sleep(1); \
;     if ((++_sp & 255u) == 0u) { if (xb_ld(&(bar)[XB_TMO])) break; if (_sp > XB_SPIN_CAP) { atomicAdd(&(bar)[XB_TMO], 1u); break; } } } } while (0)
; DEVI void xcd_barrier(unsigned* bar, volatile LAS unsigned* st) {
;     ...
;             else XB_SPIN(xb_ld(&bar[XB_TOPGEN]) == tg, bar);
;             __builtin_amdgcn_fence(__ATOMIC_ACQUIRE, "agent");
;             xb_add(&bar[XB_XGEN(x)], 1u);
;             asm volatile("s_waitcnt vmcnt(0)" ::: "memory");
.LBB0_199:
	s_or_b64 exec, exec, s[4:5]
	s_mov_b64 s[4:5], exec
	v_mbcnt_lo_u32_b32 v0, s4, 0
	v_mbcnt_hi_u32_b32 v0, s5, v0
	v_cmp_eq_u32_e32 vcc, 0, v0
	s_waitcnt vmcnt(0)
	buffer_inv sc1
	s_and_saveexec_b64 s[6:7], vcc
	s_cbranch_execz .LBB0_201
	s_bcnt1_i32_b64 s4, s[4:5]
	v_mov_b32_e32 v0, 0x2000
	v_mov_b32_e32 v1, s4
.LBB0_201:
	s_or_b64 exec, exec, s[6:7]
	s_waitcnt vmcnt(0)

; DEVI unsigned xb_ld(unsigned* p)              { return __hip_atomic_load(p, __ATOMIC_RELAXED, __HIP_MEMORY_SCOPE_AGENT); }
; DEVI unsigned xb_add(unsigned* p, unsigned v) { return __hip_atomic_fetch_add(p, v, __ATOMIC_RELAXED, __HIP_MEMORY_SCOPE_AGENT); }
; #define XB_SPIN(cond, bar) do { unsigned _sp = 0; while (cond) { __builtin_amdgcn_s_sleep(1); \
;     if ((++_sp & 255u) == 0u) { if (xb_ld(&(bar)[XB_TMO])) break; if (_sp > XB_SPIN_CAP) { atomicAdd(&(bar)[XB_TMO], 1u); break; } } } } while (0)
; DEVI void xcd_barrier(unsigned* bar, volatile LAS unsigned* st) {
;     ...
;             else XB_SPIN(xb_ld(&bar[XB_TOPGEN]) == tg, bar);
;             __builtin_amdgcn_fence(__ATOMIC_ACQUIRE, "agent");
;             xb_add(&bar[XB_XGEN(x)], 1u);
;             asm volatile("s_waitcnt vmcnt(0)" ::: "memory");
.LBB0_287:
	s_or_b64 exec, exec, s[4:5]
	s_mov_b64 s[4:5], exec
	v_mbcnt_lo_u32_b32 v0, s4, 0
	v_mbcnt_hi_u32_b32 v0, s5, v0
	v_cmp_eq_u32_e32 vcc, 0, v0
	s_waitcnt vmcnt(0)
	buffer_inv sc1
	s_and_saveexec_b64 s[6:7], vcc
	s_cbranch_execz .LBB0_289
	s_bcnt1_i32_b64 s4, s[4:5]
	v_mov_b32_e32 v0, 0x2000
	v_mov_b32_e32 v1, s4
.LBB0_289:
	s_or_b64 exec, exec, s[6:7]
	s_waitcnt vmcnt(0)

; DEVI unsigned xb_ld(unsigned* p)              { return __hip_atomic_load(p, __ATOMIC_RELAXED, __HIP_MEMORY_SCOPE_AGENT); }
; DEVI unsigned xb_add(unsigned* p, unsigned v) { return __hip_atomic_fetch_add(p, v, __ATOMIC_RELAXED, __HIP_MEMORY_SCOPE_AGENT); }
; #define XB_SPIN(cond, bar) do { unsigned _sp = 0; while (cond) { __builtin_amdgcn_s_sleep(1); \
;     if ((++_sp & 255u) == 0u) { if (xb_ld(&(bar)[XB_TMO])) break; if (_sp > XB_SPIN_CAP) { atomicAdd(&(bar)[XB_TMO], 1u); break; } } } } while (0)
; DEVI void xcd_barrier(unsigned* bar, volatile LAS unsigned* st) {
;     ...
;             else XB_SPIN(xb_ld(&bar[XB_TOPGEN]) == tg, bar);
;             __builtin_amdgcn_fence(__ATOMIC_ACQUIRE, "agent");
;             xb_add(&bar[XB_XGEN(x)], 1u);
;             asm volatile("s_waitcnt vmcnt(0)" ::: "memory");
.LBB0_384:
	s_or_b64 exec, exec, s[4:5]
	s_mov_b64 s[4:5], exec
	v_mbcnt_lo_u32_b32 v0, s4, 0
	v_mbcnt_hi_u32_b32 v0, s5, v0
	v_cmp_eq_u32_e32 vcc, 0, v0
	s_waitcnt vmcnt(0)
	buffer_inv sc1
	s_and_saveexec_b64 s[6:7], vcc
	s_cbranch_execz .LBB0_386
	s_bcnt1_i32_b64 s4, s[4:5]
	v_mov_b32_e32 v0, 0x2000
	v_mov_b32_e32 v1, s4
.LBB0_386:
	s_or_b64 exec, exec, s[6:7]
	s_waitcnt vmcnt(0)

; DEVI unsigned xb_ld(unsigned* p)              { return __hip_atomic_load(p, __ATOMIC_RELAXED, __HIP_MEMORY_SCOPE_AGENT); }
; DEVI unsigned xb_add(unsigned* p, unsigned v) { return __hip_atomic_fetch_add(p, v, __ATOMIC_RELAXED, __HIP_MEMORY_SCOPE_AGENT); }
; #define XB_SPIN(cond, bar) do { unsigned _sp = 0; while (cond) { __builtin_amdgcn_s_sleep(1); \
;     if ((++_sp & 255u) == 0u) { if (xb_ld(&(bar)[XB_TMO])) break; if (_sp > XB_SPIN_CAP) { atomicAdd(&(bar)[XB_TMO], 1u); break; } } } } while (0)
; DEVI void xcd_barrier(unsigned* bar, volatile LAS unsigned* st) {
;     ...
;             else XB_SPIN(xb_ld(&bar[XB_TOPGEN]) == tg, bar);
;             __builtin_amdgcn_fence(__ATOMIC_ACQUIRE, "agent");
;             xb_add(&bar[XB_XGEN(x)], 1u);
;             asm volatile("s_waitcnt vmcnt(0)" ::: "memory");
.LBB0_482:
	s_or_b64 exec, exec, s[4:5]
	s_mov_b64 s[4:5], exec
	v_mbcnt_lo_u32_b32 v0, s4, 0
	v_mbcnt_hi_u32_b32 v0, s5, v0
	v_cmp_eq_u32_e32 vcc, 0, v0
	s_waitcnt vmcnt(0)
	buffer_inv sc1
	s_and_saveexec_b64 s[6:7], vcc
	s_cbranch_execz .LBB0_484
	s_bcnt1_i32_b64 s4, s[4:5]
	v_mov_b32_e32 v0, 0x2000
	v_mov_b32_e32 v1, s4
.LBB0_484:
	s_or_b64 exec, exec, s[6:7]
	s_waitcnt vmcnt(0)

; DEVI unsigned xb_ld(unsigned* p)              { return __hip_atomic_load(p, __ATOMIC_RELAXED, __HIP_MEMORY_SCOPE_AGENT); }
; DEVI unsigned xb_add(unsigned* p, unsigned v) { return __hip_atomic_fetch_add(p, v, __ATOMIC_RELAXED, __HIP_MEMORY_SCOPE_AGENT); }
; #define XB_SPIN(cond, bar) do { unsigned _sp = 0; while (cond) { __builtin_amdgcn_s_sleep(1); \
;     if ((++_sp & 255u) == 0u) { if (xb_ld(&(bar)[XB_TMO])) break; if (_sp > XB_SPIN_CAP) { atomicAdd(&(bar)[XB_TMO], 1u); break; } } } } while (0)
; DEVI void xcd_barrier(unsigned* bar, volatile LAS unsigned* st) {
;     ...
;             else XB_SPIN(xb_ld(&bar[XB_TOPGEN]) == tg, bar);
;             __builtin_amdgcn_fence(__ATOMIC_ACQUIRE, "agent");
;             xb_add(&bar[XB_XGEN(x)], 1u);
;             asm volatile("s_waitcnt vmcnt(0)" ::: "memory");
.LBB0_640:
	s_or_b64 exec, exec, s[4:5]
	s_mov_b64 s[4:5], exec
	v_mbcnt_lo_u32_b32 v0, s4, 0
	v_mbcnt_hi_u32_b32 v0, s5, v0
	v_cmp_eq_u32_e32 vcc, 0, v0
	s_waitcnt vmcnt(0)
	buffer_inv sc1
	s_and_saveexec_b64 s[6:7], vcc
	s_cbranch_execz .LBB0_642
	s_bcnt1_i32_b64 s4, s[4:5]
	v_mov_b32_e32 v0, 0x2000
	v_mov_b32_e32 v1, s4
.LBB0_642:
	s_or_b64 exec, exec, s[6:7]
	s_waitcnt vmcnt(0)

; DEVI unsigned xb_ld(unsigned* p)              { return __hip_atomic_load(p, __ATOMIC_RELAXED, __HIP_MEMORY_SCOPE_AGENT); }
; DEVI unsigned xb_add(unsigned* p, unsigned v) { return __hip_atomic_fetch_add(p, v, __ATOMIC_RELAXED, __HIP_MEMORY_SCOPE_AGENT); }
; #define XB_SPIN(cond, bar) do { unsigned _sp = 0; while (cond) { __builtin_amdgcn_s_sleep(1); \
;     if ((++_sp & 255u) == 0u) { if (xb_ld(&(bar)[XB_TMO])) break; if (_sp > XB_SPIN_CAP) { atomicAdd(&(bar)[XB_TMO], 1u); break; } } } } while (0)
; DEVI void xcd_barrier(unsigned* bar, volatile LAS unsigned* st) {
;     ...
;             else XB_SPIN(xb_ld(&bar[XB_TOPGEN]) == tg, bar);
;             __builtin_amdgcn_fence(__ATOMIC_ACQUIRE, "agent");
;             xb_add(&bar[XB_XGEN(x)], 1u);
;             asm volatile("s_waitcnt vmcnt(0)" ::: "memory");
.LBB0_750:
	s_or_b64 exec, exec, s[4:5]
	s_mov_b64 s[4:5], exec
	v_mbcnt_lo_u32_b32 v0, s4, 0
	v_mbcnt_hi_u32_b32 v0, s5, v0
	v_cmp_eq_u32_e32 vcc, 0, v0
	s_waitcnt vmcnt(0)
	buffer_inv sc1
	s_and_saveexec_b64 s[6:7], vcc
	s_cbranch_execz .LBB0_752
	s_bcnt1_i32_b64 s4, s[4:5]
	v_mov_b32_e32 v0, 0x2000
	v_mov_b32_e32 v1, s4
.LBB0_752:
	s_or_b64 exec, exec, s[6:7]
	s_waitcnt vmcnt(0)

; DEVI unsigned xb_ld(unsigned* p)              { return __hip_atomic_load(p, __ATOMIC_RELAXED, __HIP_MEMORY_SCOPE_AGENT); }
; DEVI unsigned xb_add(unsigned* p, unsigned v) { return __hip_atomic_fetch_add(p, v, __ATOMIC_RELAXED, __HIP_MEMORY_SCOPE_AGENT); }
; #define XB_SPIN(cond, bar) do { unsigned _sp = 0; while (cond) { __builtin_amdgcn_s_sleep(1); \
;     if ((++_sp & 255u) == 0u) { if (xb_ld(&(bar)[XB_TMO])) break; if (_sp > XB_SPIN_CAP) { atomicAdd(&(bar)[XB_TMO], 1u); break; } } } } while (0)
; DEVI void xcd_barrier(unsigned* bar, volatile LAS unsigned* st) {
;     ...
;             else XB_SPIN(xb_ld(&bar[XB_TOPGEN]) == tg, bar);
;             __builtin_amdgcn_fence(__ATOMIC_ACQUIRE, "agent");
;             xb_add(&bar[XB_XGEN(x)], 1u);
;             asm volatile("s_waitcnt vmcnt(0)" ::: "memory");
.LBB0_953:
	s_or_b64 exec, exec, s[4:5]
	s_mov_b64 s[4:5], exec
	v_mbcnt_lo_u32_b32 v0, s4, 0
	v_mbcnt_hi_u32_b32 v0, s5, v0
	v_cmp_eq_u32_e32 vcc, 0, v0
	s_waitcnt vmcnt(0)
	buffer_inv sc1
	s_and_saveexec_b64 s[6:7], vcc
	s_cbranch_execz .LBB0_955
	s_bcnt1_i32_b64 s4, s[4:5]
	v_mov_b32_e32 v0, 0x2000
	v_mov_b32_e32 v1, s4
.LBB0_955:
	s_or_b64 exec, exec, s[6:7]
	s_waitcnt vmcnt(0)

; DEVI unsigned xb_ld(unsigned* p)              { return __hip_atomic_load(p, __ATOMIC_RELAXED, __HIP_MEMORY_SCOPE_AGENT); }
; DEVI unsigned xb_add(unsigned* p, unsigned v) { return __hip_atomic_fetch_add(p, v, __ATOMIC_RELAXED, __HIP_MEMORY_SCOPE_AGENT); }
; #define XB_SPIN(cond, bar) do { unsigned _sp = 0; while (cond) { __builtin_amdgcn_s_sleep(1); \
;     if ((++_sp & 255u) == 0u) { if (xb_ld(&(bar)[XB_TMO])) break; if (_sp > XB_SPIN_CAP) { atomicAdd(&(bar)[XB_TMO], 1u); break; } } } } while (0)
; DEVI void xcd_barrier(unsigned* bar, volatile LAS unsigned* st) {
;     ...
;             else XB_SPIN(xb_ld(&bar[XB_TOPGEN]) == tg, bar);
;             __builtin_amdgcn_fence(__ATOMIC_ACQUIRE, "agent");
;             xb_add(&bar[XB_XGEN(x)], 1u);
;             asm volatile("s_waitcnt vmcnt(0)" ::: "memory");
.LBB0_1021:
	s_or_b64 exec, exec, s[4:5]
	s_mov_b64 s[4:5], exec
	v_mbcnt_lo_u32_b32 v0, s4, 0
	v_mbcnt_hi_u32_b32 v0, s5, v0
	v_cmp_eq_u32_e32 vcc, 0, v0
	s_waitcnt vmcnt(0)
	buffer_inv sc1
	s_and_saveexec_b64 s[6:7], vcc
	s_cbranch_execz .LBB0_1023
	s_bcnt1_i32_b64 s4, s[4:5]
	v_mov_b32_e32 v0, 0x2000
	v_mov_b32_e32 v1, s4
.LBB0_1023:
	s_or_b64 exec, exec, s[6:7]
	s_waitcnt vmcnt(0)

; DEVI unsigned xb_ld(unsigned* p)              { return __hip_atomic_load(p, __ATOMIC_RELAXED, __HIP_MEMORY_SCOPE_AGENT); }
; DEVI unsigned xb_add(unsigned* p, unsigned v) { return __hip_atomic_fetch_add(p, v, __ATOMIC_RELAXED, __HIP_MEMORY_SCOPE_AGENT); }
; #define XB_SPIN(cond, bar) do { unsigned _sp = 0; while (cond) { __builtin_amdgcn_s_sleep(1); \
;     if ((++_sp & 255u) == 0u) { if (xb_ld(&(bar)[XB_TMO])) break; if (_sp > XB_SPIN_CAP) { atomicAdd(&(bar)[XB_TMO], 1u); break; } } } } while (0)
; DEVI void xcd_barrier(unsigned* bar, volatile LAS unsigned* st) {
;     ...
;             else XB_SPIN(xb_ld(&bar[XB_TOPGEN]) == tg, bar);
;             __builtin_amdgcn_fence(__ATOMIC_ACQUIRE, "agent");
;             xb_add(&bar[XB_XGEN(x)], 1u);
;             asm volatile("s_waitcnt vmcnt(0)" ::: "memory");
.LBB0_1109:
	s_or_b64 exec, exec, s[4:5]
	s_mov_b64 s[4:5], exec
	v_mbcnt_lo_u32_b32 v0, s4, 0
	v_mbcnt_hi_u32_b32 v0, s5, v0
	v_cmp_eq_u32_e32 vcc, 0, v0
	s_waitcnt vmcnt(0)
	buffer_inv sc1
	s_and_saveexec_b64 s[6:7], vcc
	s_cbranch_execz .LBB0_1111
	s_bcnt1_i32_b64 s4, s[4:5]
	v_mov_b32_e32 v0, 0x2000
	v_mov_b32_e32 v1, s4
.LBB0_1111:
	s_or_b64 exec, exec, s[6:7]
	s_waitcnt vmcnt(0)

; DEVI unsigned xb_ld(unsigned* p)              { return __hip_atomic_load(p, __ATOMIC_RELAXED, __HIP_MEMORY_SCOPE_AGENT); }
; DEVI unsigned xb_add(unsigned* p, unsigned v) { return __hip_atomic_fetch_add(p, v, __ATOMIC_RELAXED, __HIP_MEMORY_SCOPE_AGENT); }
; #define XB_SPIN(cond, bar) do { unsigned _sp = 0; while (cond) { __builtin_amdgcn_s_sleep(1); \
;     if ((++_sp & 255u) == 0u) { if (xb_ld(&(bar)[XB_TMO])) break; if (_sp > XB_SPIN_CAP) { atomicAdd(&(bar)[XB_TMO], 1u); break; } } } } while (0)
; DEVI void xcd_barrier(unsigned* bar, volatile LAS unsigned* st) {
;     ...
;             else XB_SPIN(xb_ld(&bar[XB_TOPGEN]) == tg, bar);
;             __builtin_amdgcn_fence(__ATOMIC_ACQUIRE, "agent");
;             xb_add(&bar[XB_XGEN(x)], 1u);
;             asm volatile("s_waitcnt vmcnt(0)" ::: "memory");
.LBB0_1206:
	s_or_b64 exec, exec, s[4:5]
	s_mov_b64 s[4:5], exec
	v_mbcnt_lo_u32_b32 v0, s4, 0
	v_mbcnt_hi_u32_b32 v0, s5, v0
	v_cmp_eq_u32_e32 vcc, 0, v0
	s_waitcnt vmcnt(0)
	buffer_inv sc1
	s_and_saveexec_b64 s[6:7], vcc
	s_cbranch_execz .LBB0_1208
	s_bcnt1_i32_b64 s4, s[4:5]
	v_mov_b32_e32 v0, 0x2000
	v_mov_b32_e32 v1, s4
.LBB0_1208:
	s_or_b64 exec, exec, s[6:7]
	s_waitcnt vmcnt(0)

; DEVI unsigned xb_ld(unsigned* p)              { return __hip_atomic_load(p, __ATOMIC_RELAXED, __HIP_MEMORY_SCOPE_AGENT); }
; DEVI unsigned xb_add(unsigned* p, unsigned v) { return __hip_atomic_fetch_add(p, v, __ATOMIC_RELAXED, __HIP_MEMORY_SCOPE_AGENT); }
; #define XB_SPIN(cond, bar) do { unsigned _sp = 0; while (cond) { __builtin_amdgcn_s_sleep(1); \
;     if ((++_sp & 255u) == 0u) { if (xb_ld(&(bar)[XB_TMO])) break; if (_sp > XB_SPIN_CAP) { atomicAdd(&(bar)[XB_TMO], 1u); break; } } } } while (0)
; DEVI void xcd_barrier(unsigned* bar, volatile LAS unsigned* st) {
;     ...
;             else XB_SPIN(xb_ld(&bar[XB_TOPGEN]) == tg, bar);
;             __builtin_amdgcn_fence(__ATOMIC_ACQUIRE, "agent");
;             xb_add(&bar[XB_XGEN(x)], 1u);
;             asm volatile("s_waitcnt vmcnt(0)" ::: "memory");
.LBB0_1304:
	s_or_b64 exec, exec, s[4:5]
	s_mov_b64 s[4:5], exec
	v_mbcnt_lo_u32_b32 v0, s4, 0
	v_mbcnt_hi_u32_b32 v0, s5, v0
	v_cmp_eq_u32_e32 vcc, 0, v0
	s_waitcnt vmcnt(0)
	buffer_inv sc1
	s_and_saveexec_b64 s[6:7], vcc
	s_cbranch_execz .LBB0_1306
	s_bcnt1_i32_b64 s4, s[4:5]
	v_mov_b32_e32 v0, 0x2000
	v_mov_b32_e32 v1, s4
.LBB0_1306:
	s_or_b64 exec, exec, s[6:7]
	s_waitcnt vmcnt(0)

; DEVI unsigned xb_ld(unsigned* p)              { return __hip_atomic_load(p, __ATOMIC_RELAXED, __HIP_MEMORY_SCOPE_AGENT); }
; DEVI unsigned xb_add(unsigned* p, unsigned v) { return __hip_atomic_fetch_add(p, v, __ATOMIC_RELAXED, __HIP_MEMORY_SCOPE_AGENT); }
; #define XB_SPIN(cond, bar) do { unsigned _sp = 0; while (cond) { __builtin_amdgcn_s_sleep(1); \
;     if ((++_sp & 255u) == 0u) { if (xb_ld(&(bar)[XB_TMO])) break; if (_sp > XB_SPIN_CAP) { atomicAdd(&(bar)[XB_TMO], 1u); break; } } } } while (0)
; DEVI void xcd_barrier(unsigned* bar, volatile LAS unsigned* st) {
;     ...
;             else XB_SPIN(xb_ld(&bar[XB_TOPGEN]) == tg, bar);
;             __builtin_amdgcn_fence(__ATOMIC_ACQUIRE, "agent");
;             xb_add(&bar[XB_XGEN(x)], 1u);
;             asm volatile("s_waitcnt vmcnt(0)" ::: "memory");
.LBB0_1398:
	s_or_b64 exec, exec, s[4:5]
	s_mov_b64 s[4:5], exec
	v_mbcnt_lo_u32_b32 v0, s4, 0
	v_mbcnt_hi_u32_b32 v0, s5, v0
	v_cmp_eq_u32_e32 vcc, 0, v0
	s_waitcnt vmcnt(0)
	buffer_inv sc1
	s_and_saveexec_b64 s[6:7], vcc
	s_cbranch_execz .LBB0_1400
	s_bcnt1_i32_b64 s4, s[4:5]
	v_mov_b32_e32 v0, 0x2000
	v_mov_b32_e32 v1, s4
.LBB0_1400:
	s_or_b64 exec, exec, s[6:7]
	s_waitcnt vmcnt(0)

; DEVI unsigned xb_ld(unsigned* p)              { return __hip_atomic_load(p, __ATOMIC_RELAXED, __HIP_MEMORY_SCOPE_AGENT); }
; DEVI unsigned xb_add(unsigned* p, unsigned v) { return __hip_atomic_fetch_add(p, v, __ATOMIC_RELAXED, __HIP_MEMORY_SCOPE_AGENT); }
; #define XB_SPIN(cond, bar) do { unsigned _sp = 0; while (cond) { __builtin_amdgcn_s_sleep(1); \
;     if ((++_sp & 255u) == 0u) { if (xb_ld(&(bar)[XB_TMO])) break; if (_sp > XB_SPIN_CAP) { atomicAdd(&(bar)[XB_TMO], 1u); break; } } } } while (0)
; DEVI void xcd_barrier(unsigned* bar, volatile LAS unsigned* st) {
;     ...
;             else XB_SPIN(xb_ld(&bar[XB_TOPGEN]) == tg, bar);
;             __builtin_amdgcn_fence(__ATOMIC_ACQUIRE, "agent");
;             xb_add(&bar[XB_XGEN(x)], 1u);
;             asm volatile("s_waitcnt vmcnt(0)" ::: "memory");
.LBB0_1492:
	s_or_b64 exec, exec, s[6:7]
	s_mov_b64 s[6:7], exec
	v_mbcnt_lo_u32_b32 v0, s6, 0
	v_mbcnt_hi_u32_b32 v0, s7, v0
	v_cmp_eq_u32_e32 vcc, 0, v0
	s_waitcnt vmcnt(0)
	buffer_inv sc1
	s_and_saveexec_b64 s[8:9], vcc
	s_cbranch_execz .LBB0_1494
	s_bcnt1_i32_b64 s6, s[6:7]
	v_mov_b32_e32 v0, 0x2000
	v_mov_b32_e32 v1, s6
.LBB0_1494:
	s_or_b64 exec, exec, s[8:9]
	s_waitcnt vmcnt(0)

; DEVI unsigned xb_ld(unsigned* p)              { return __hip_atomic_load(p, __ATOMIC_RELAXED, __HIP_MEMORY_SCOPE_AGENT); }
; DEVI unsigned xb_add(unsigned* p, unsigned v) { return __hip_atomic_fetch_add(p, v, __ATOMIC_RELAXED, __HIP_MEMORY_SCOPE_AGENT); }
; #define XB_SPIN(cond, bar) do { unsigned _sp = 0; while (cond) { __builtin_amdgcn_s_sleep(1); \
;     if ((++_sp & 255u) == 0u) { if (xb_ld(&(bar)[XB_TMO])) break; if (_sp > XB_SPIN_CAP) { atomicAdd(&(bar)[XB_TMO], 1u); break; } } } } while (0)
; DEVI void xcd_barrier(unsigned* bar, volatile LAS unsigned* st) {
;     ...
;             else XB_SPIN(xb_ld(&bar[XB_TOPGEN]) == tg, bar);
;             __builtin_amdgcn_fence(__ATOMIC_ACQUIRE, "agent");
;             xb_add(&bar[XB_XGEN(x)], 1u);
;             asm volatile("s_waitcnt vmcnt(0)" ::: "memory");
.LBB0_1607:
	s_or_b64 exec, exec, s[4:5]
	s_mov_b64 s[4:5], exec
	v_mbcnt_lo_u32_b32 v0, s4, 0
	v_mbcnt_hi_u32_b32 v0, s5, v0
	v_cmp_eq_u32_e32 vcc, 0, v0
	s_waitcnt vmcnt(0)
	buffer_inv sc1
	s_and_saveexec_b64 s[6:7], vcc
	s_cbranch_execz .LBB0_1609
	s_bcnt1_i32_b64 s4, s[4:5]
	v_mov_b32_e32 v0, 0x2000
	v_mov_b32_e32 v1, s4
.LBB0_1609:
	s_or_b64 exec, exec, s[6:7]
	s_waitcnt vmcnt(0)

; DEVI unsigned xb_ld(unsigned* p)              { return __hip_atomic_load(p, __ATOMIC_RELAXED, __HIP_MEMORY_SCOPE_AGENT); }
; DEVI unsigned xb_add(unsigned* p, unsigned v) { return __hip_atomic_fetch_add(p, v, __ATOMIC_RELAXED, __HIP_MEMORY_SCOPE_AGENT); }
; #define XB_SPIN(cond, bar) do { unsigned _sp = 0; while (cond) { __builtin_amdgcn_s_sleep(1); \
;     if ((++_sp & 255u) == 0u) { if (xb_ld(&(bar)[XB_TMO])) break; if (_sp > XB_SPIN_CAP) { atomicAdd(&(bar)[XB_TMO], 1u); break; } } } } while (0)
; DEVI void xcd_barrier(unsigned* bar, volatile LAS unsigned* st) {
;     ...
;             else XB_SPIN(xb_ld(&bar[XB_TOPGEN]) == tg, bar);
;             __builtin_amdgcn_fence(__ATOMIC_ACQUIRE, "agent");
;             xb_add(&bar[XB_XGEN(x)], 1u);
;             asm volatile("s_waitcnt vmcnt(0)" ::: "memory");
.LBB0_1675:
	s_or_b64 exec, exec, s[4:5]
	s_mov_b64 s[4:5], exec
	v_mbcnt_lo_u32_b32 v0, s4, 0
	v_mbcnt_hi_u32_b32 v0, s5, v0
	v_cmp_eq_u32_e32 vcc, 0, v0
	s_waitcnt vmcnt(0)
	buffer_inv sc1
	s_and_saveexec_b64 s[6:7], vcc
	s_cbranch_execz .LBB0_1677
	s_bcnt1_i32_b64 s4, s[4:5]
	v_mov_b32_e32 v0, 0x2000
	v_mov_b32_e32 v1, s4
.LBB0_1677:
	s_or_b64 exec, exec, s[6:7]
	s_waitcnt vmcnt(0)

; DEVI unsigned xb_ld(unsigned* p)              { return __hip_atomic_load(p, __ATOMIC_RELAXED, __HIP_MEMORY_SCOPE_AGENT); }
; DEVI unsigned xb_add(unsigned* p, unsigned v) { return __hip_atomic_fetch_add(p, v, __ATOMIC_RELAXED, __HIP_MEMORY_SCOPE_AGENT); }
; #define XB_SPIN(cond, bar) do { unsigned _sp = 0; while (cond) { __builtin_amdgcn_s_sleep(1); \
;     if ((++_sp & 255u) == 0u) { if (xb_ld(&(bar)[XB_TMO])) break; if (_sp > XB_SPIN_CAP) { atomicAdd(&(bar)[XB_TMO], 1u); break; } } } } while (0)
; DEVI void xcd_barrier(unsigned* bar, volatile LAS unsigned* st) {
;     ...
;             else XB_SPIN(xb_ld(&bar[XB_TOPGEN]) == tg, bar);
;             __builtin_amdgcn_fence(__ATOMIC_ACQUIRE, "agent");
;             xb_add(&bar[XB_XGEN(x)], 1u);
;             asm volatile("s_waitcnt vmcnt(0)" ::: "memory");
.LBB0_1763:
	s_or_b64 exec, exec, s[4:5]
	s_mov_b64 s[4:5], exec
	v_mbcnt_lo_u32_b32 v0, s4, 0
	v_mbcnt_hi_u32_b32 v0, s5, v0
	v_cmp_eq_u32_e32 vcc, 0, v0
	s_waitcnt vmcnt(0)
	buffer_inv sc1
	s_and_saveexec_b64 s[6:7], vcc
	s_cbranch_execz .LBB0_1765
	s_bcnt1_i32_b64 s4, s[4:5]
	v_mov_b32_e32 v0, 0x2000
	v_mov_b32_e32 v1, s4
.LBB0_1765:
	s_or_b64 exec, exec, s[6:7]
	s_waitcnt vmcnt(0)

; DEVI unsigned xb_ld(unsigned* p)              { return __hip_atomic_load(p, __ATOMIC_RELAXED, __HIP_MEMORY_SCOPE_AGENT); }
; DEVI unsigned xb_add(unsigned* p, unsigned v) { return __hip_atomic_fetch_add(p, v, __ATOMIC_RELAXED, __HIP_MEMORY_SCOPE_AGENT); }
; #define XB_SPIN(cond, bar) do { unsigned _sp = 0; while (cond) { __builtin_amdgcn_s_sleep(1); \
;     if ((++_sp & 255u) == 0u) { if (xb_ld(&(bar)[XB_TMO])) break; if (_sp > XB_SPIN_CAP) { atomicAdd(&(bar)[XB_TMO], 1u); break; } } } } while (0)
; DEVI void xcd_barrier(unsigned* bar, volatile LAS unsigned* st) {
;     ...
;             else XB_SPIN(xb_ld(&bar[XB_TOPGEN]) == tg, bar);
;             __builtin_amdgcn_fence(__ATOMIC_ACQUIRE, "agent");
;             xb_add(&bar[XB_XGEN(x)], 1u);
;             asm volatile("s_waitcnt vmcnt(0)" ::: "memory");
.LBB0_1860:
	s_or_b64 exec, exec, s[4:5]
	s_mov_b64 s[4:5], exec
	v_mbcnt_lo_u32_b32 v0, s4, 0
	v_mbcnt_hi_u32_b32 v0, s5, v0
	v_cmp_eq_u32_e32 vcc, 0, v0
	s_waitcnt vmcnt(0)
	buffer_inv sc1
	s_and_saveexec_b64 s[6:7], vcc
	s_cbranch_execz .LBB0_1862
	s_bcnt1_i32_b64 s4, s[4:5]
	v_mov_b32_e32 v0, 0x2000
	v_mov_b32_e32 v1, s4
.LBB0_1862:
	s_or_b64 exec, exec, s[6:7]
	s_waitcnt vmcnt(0)

; DEVI unsigned xb_ld(unsigned* p)              { return __hip_atomic_load(p, __ATOMIC_RELAXED, __HIP_MEMORY_SCOPE_AGENT); }
; DEVI unsigned xb_add(unsigned* p, unsigned v) { return __hip_atomic_fetch_add(p, v, __ATOMIC_RELAXED, __HIP_MEMORY_SCOPE_AGENT); }
; #define XB_SPIN(cond, bar) do { unsigned _sp = 0; while (cond) { __builtin_amdgcn_s_sleep(1); \
;     if ((++_sp & 255u) == 0u) { if (xb_ld(&(bar)[XB_TMO])) break; if (_sp > XB_SPIN_CAP) { atomicAdd(&(bar)[XB_TMO], 1u); break; } } } } while (0)
; DEVI void xcd_barrier(unsigned* bar, volatile LAS unsigned* st) {
;     ...
;             else XB_SPIN(xb_ld(&bar[XB_TOPGEN]) == tg, bar);
;             __builtin_amdgcn_fence(__ATOMIC_ACQUIRE, "agent");
;             xb_add(&bar[XB_XGEN(x)], 1u);
;             asm volatile("s_waitcnt vmcnt(0)" ::: "memory");
.LBB0_1958:
	s_or_b64 exec, exec, s[4:5]
	s_mov_b64 s[4:5], exec
	v_mbcnt_lo_u32_b32 v0, s4, 0
	v_mbcnt_hi_u32_b32 v0, s5, v0
	v_cmp_eq_u32_e32 vcc, 0, v0
	s_waitcnt vmcnt(0)
	buffer_inv sc1
	s_and_saveexec_b64 s[6:7], vcc
	s_cbranch_execz .LBB0_1960
	s_bcnt1_i32_b64 s4, s[4:5]
	v_mov_b32_e32 v0, 0x2000
	v_mov_b32_e32 v1, s4
.LBB0_1960:
	s_or_b64 exec, exec, s[6:7]
	s_waitcnt vmcnt(0)

; DEVI unsigned xb_ld(unsigned* p)              { return __hip_atomic_load(p, __ATOMIC_RELAXED, __HIP_MEMORY_SCOPE_AGENT); }
; DEVI unsigned xb_add(unsigned* p, unsigned v) { return __hip_atomic_fetch_add(p, v, __ATOMIC_RELAXED, __HIP_MEMORY_SCOPE_AGENT); }
; #define XB_SPIN(cond, bar) do { unsigned _sp = 0; while (cond) { __builtin_amdgcn_s_sleep(1); \
;     if ((++_sp & 255u) == 0u) { if (xb_ld(&(bar)[XB_TMO])) break; if (_sp > XB_SPIN_CAP) { atomicAdd(&(bar)[XB_TMO], 1u); break; } } } } while (0)
; DEVI void xcd_barrier(unsigned* bar, volatile LAS unsigned* st) {
;     ...
;             else XB_SPIN(xb_ld(&bar[XB_TOPGEN]) == tg, bar);
;             __builtin_amdgcn_fence(__ATOMIC_ACQUIRE, "agent");
;             xb_add(&bar[XB_XGEN(x)], 1u);
;             asm volatile("s_waitcnt vmcnt(0)" ::: "memory");
.LBB0_2052:
	s_or_b64 exec, exec, s[4:5]
	s_mov_b64 s[4:5], exec
	v_mbcnt_lo_u32_b32 v0, s4, 0
	v_mbcnt_hi_u32_b32 v0, s5, v0
	v_cmp_eq_u32_e32 vcc, 0, v0
	s_waitcnt vmcnt(0)
	buffer_inv sc1
	s_and_saveexec_b64 s[6:7], vcc
	s_cbranch_execz .LBB0_2054
	s_bcnt1_i32_b64 s4, s[4:5]
	v_mov_b32_e32 v0, 0x2000
	v_mov_b32_e32 v1, s4
.LBB0_2054:
	s_or_b64 exec, exec, s[6:7]
	s_waitcnt vmcnt(0)

; DEVI unsigned xb_ld(unsigned* p)              { return __hip_atomic_load(p, __ATOMIC_RELAXED, __HIP_MEMORY_SCOPE_AGENT); }
; DEVI unsigned xb_add(unsigned* p, unsigned v) { return __hip_atomic_fetch_add(p, v, __ATOMIC_RELAXED, __HIP_MEMORY_SCOPE_AGENT); }
; #define XB_SPIN(cond, bar) do { unsigned _sp = 0; while (cond) { __builtin_amdgcn_s_sleep(1); \
;     if ((++_sp & 255u) == 0u) { if (xb_ld(&(bar)[XB_TMO])) break; if (_sp > XB_SPIN_CAP) { atomicAdd(&(bar)[XB_TMO], 1u); break; } } } } while (0)
; DEVI void xcd_barrier(unsigned* bar, volatile LAS unsigned* st) {
;     ...
;             else XB_SPIN(xb_ld(&bar[XB_TOPGEN]) == tg, bar);
;             __builtin_amdgcn_fence(__ATOMIC_ACQUIRE, "agent");
;             xb_add(&bar[XB_XGEN(x)], 1u);
;             asm volatile("s_waitcnt vmcnt(0)" ::: "memory");
.LBB0_2146:
	s_or_b64 exec, exec, s[6:7]
	s_mov_b64 s[6:7], exec
	v_mbcnt_lo_u32_b32 v0, s6, 0
	v_mbcnt_hi_u32_b32 v0, s7, v0
	v_cmp_eq_u32_e32 vcc, 0, v0
	s_waitcnt vmcnt(0)
	buffer_inv sc1
	s_and_saveexec_b64 s[8:9], vcc
	s_cbranch_execz .LBB0_2148
	s_bcnt1_i32_b64 s6, s[6:7]
	v_mov_b32_e32 v0, 0x2000
	v_mov_b32_e32 v1, s6
.LBB0_2148:
	s_or_b64 exec, exec, s[8:9]
	s_waitcnt vmcnt(0)

; DEVI unsigned xb_ld(unsigned* p)              { return __hip_atomic_load(p, __ATOMIC_RELAXED, __HIP_MEMORY_SCOPE_AGENT); }
; DEVI unsigned xb_add(unsigned* p, unsigned v) { return __hip_atomic_fetch_add(p, v, __ATOMIC_RELAXED, __HIP_MEMORY_SCOPE_AGENT); }
; #define XB_SPIN(cond, bar) do { unsigned _sp = 0; while (cond) { __builtin_amdgcn_s_sleep(1); \
;     if ((++_sp & 255u) == 0u) { if (xb_ld(&(bar)[XB_TMO])) break; if (_sp > XB_SPIN_CAP) { atomicAdd(&(bar)[XB_TMO], 1u); break; } } } } while (0)
; DEVI void xcd_barrier(unsigned* bar, volatile LAS unsigned* st) {
;     ...
;             else XB_SPIN(xb_ld(&bar[XB_TOPGEN]) == tg, bar);
;             __builtin_amdgcn_fence(__ATOMIC_ACQUIRE, "agent");
;             xb_add(&bar[XB_XGEN(x)], 1u);
;             asm volatile("s_waitcnt vmcnt(0)" ::: "memory");
.LBB0_2261:
	s_or_b64 exec, exec, s[4:5]
	s_mov_b64 s[4:5], exec
	v_mbcnt_lo_u32_b32 v0, s4, 0
	v_mbcnt_hi_u32_b32 v0, s5, v0
	v_cmp_eq_u32_e32 vcc, 0, v0
	s_waitcnt vmcnt(0)
	buffer_inv sc1
	s_and_saveexec_b64 s[6:7], vcc
	s_cbranch_execz .LBB0_2263
	s_bcnt1_i32_b64 s4, s[4:5]
	v_mov_b32_e32 v0, 0x2000
	v_mov_b32_e32 v1, s4
.LBB0_2263:
	s_or_b64 exec, exec, s[6:7]
	s_waitcnt vmcnt(0)

; DEVI unsigned xb_ld(unsigned* p)              { return __hip_atomic_load(p, __ATOMIC_RELAXED, __HIP_MEMORY_SCOPE_AGENT); }
; DEVI unsigned xb_add(unsigned* p, unsigned v) { return __hip_atomic_fetch_add(p, v, __ATOMIC_RELAXED, __HIP_MEMORY_SCOPE_AGENT); }
; #define XB_SPIN(cond, bar) do { unsigned _sp = 0; while (cond) { __builtin_amdgcn_s_sleep(1); \
;     if ((++_sp & 255u) == 0u) { if (xb_ld(&(bar)[XB_TMO])) break; if (_sp > XB_SPIN_CAP) { atomicAdd(&(bar)[XB_TMO], 1u); break; } } } } while (0)
; DEVI void xcd_barrier(unsigned* bar, volatile LAS unsigned* st) {
;     ...
;             else XB_SPIN(xb_ld(&bar[XB_TOPGEN]) == tg, bar);
;             __builtin_amdgcn_fence(__ATOMIC_ACQUIRE, "agent");
;             xb_add(&bar[XB_XGEN(x)], 1u);
;             asm volatile("s_waitcnt vmcnt(0)" ::: "memory");
.LBB0_2329:
	s_or_b64 exec, exec, s[4:5]
	s_mov_b64 s[4:5], exec
	v_mbcnt_lo_u32_b32 v0, s4, 0
	v_mbcnt_hi_u32_b32 v0, s5, v0
	v_cmp_eq_u32_e32 vcc, 0, v0
	s_waitcnt vmcnt(0)
	buffer_inv sc1
	s_and_saveexec_b64 s[6:7], vcc
	s_cbranch_execz .LBB0_2331
	s_bcnt1_i32_b64 s4, s[4:5]
	v_mov_b32_e32 v0, 0x2000
	v_mov_b32_e32 v1, s4
.LBB0_2331:
	s_or_b64 exec, exec, s[6:7]
	s_waitcnt vmcnt(0)

; DEVI unsigned xb_ld(unsigned* p)              { return __hip_atomic_load(p, __ATOMIC_RELAXED, __HIP_MEMORY_SCOPE_AGENT); }
; DEVI unsigned xb_add(unsigned* p, unsigned v) { return __hip_atomic_fetch_add(p, v, __ATOMIC_RELAXED, __HIP_MEMORY_SCOPE_AGENT); }
; #define XB_SPIN(cond, bar) do { unsigned _sp = 0; while (cond) { __builtin_amdgcn_s_sleep(1); \
;     if ((++_sp & 255u) == 0u) { if (xb_ld(&(bar)[XB_TMO])) break; if (_sp > XB_SPIN_CAP) { atomicAdd(&(bar)[XB_TMO], 1u); break; } } } } while (0)
; DEVI void xcd_barrier(unsigned* bar, volatile LAS unsigned* st) {
;     ...
;             else XB_SPIN(xb_ld(&bar[XB_TOPGEN]) == tg, bar);
;             __builtin_amdgcn_fence(__ATOMIC_ACQUIRE, "agent");
;             xb_add(&bar[XB_XGEN(x)], 1u);
;             asm volatile("s_waitcnt vmcnt(0)" ::: "memory");
.LBB0_2417:
	s_or_b64 exec, exec, s[4:5]
	s_mov_b64 s[4:5], exec
	v_mbcnt_lo_u32_b32 v0, s4, 0
	v_mbcnt_hi_u32_b32 v0, s5, v0
	v_cmp_eq_u32_e32 vcc, 0, v0
	s_waitcnt vmcnt(0)
	buffer_inv sc1
	s_and_saveexec_b64 s[6:7], vcc
	s_cbranch_execz .LBB0_2419
	s_bcnt1_i32_b64 s4, s[4:5]
	v_mov_b32_e32 v0, 0x2000
	v_mov_b32_e32 v1, s4
.LBB0_2419:
	s_or_b64 exec, exec, s[6:7]
	s_waitcnt vmcnt(0)

; DEVI unsigned xb_ld(unsigned* p)              { return __hip_atomic_load(p, __ATOMIC_RELAXED, __HIP_MEMORY_SCOPE_AGENT); }
; DEVI unsigned xb_add(unsigned* p, unsigned v) { return __hip_atomic_fetch_add(p, v, __ATOMIC_RELAXED, __HIP_MEMORY_SCOPE_AGENT); }
; #define XB_SPIN(cond, bar) do { unsigned _sp = 0; while (cond) { __builtin_amdgcn_s_sleep(1); \
;     if ((++_sp & 255u) == 0u) { if (xb_ld(&(bar)[XB_TMO])) break; if (_sp > XB_SPIN_CAP) { atomicAdd(&(bar)[XB_TMO], 1u); break; } } } } while (0)
; DEVI void xcd_barrier(unsigned* bar, volatile LAS unsigned* st) {
;     ...
;             else XB_SPIN(xb_ld(&bar[XB_TOPGEN]) == tg, bar);
;             __builtin_amdgcn_fence(__ATOMIC_ACQUIRE, "agent");
;             xb_add(&bar[XB_XGEN(x)], 1u);
;             asm volatile("s_waitcnt vmcnt(0)" ::: "memory");
.LBB0_2514:
	s_or_b64 exec, exec, s[4:5]
	s_mov_b64 s[4:5], exec
	v_mbcnt_lo_u32_b32 v0, s4, 0
	v_mbcnt_hi_u32_b32 v0, s5, v0
	v_cmp_eq_u32_e32 vcc, 0, v0
	s_waitcnt vmcnt(0)
	buffer_inv sc1
	s_and_saveexec_b64 s[6:7], vcc
	s_cbranch_execz .LBB0_2516
	s_bcnt1_i32_b64 s4, s[4:5]
	v_mov_b32_e32 v0, 0x2000
	v_mov_b32_e32 v1, s4
.LBB0_2516:
	s_or_b64 exec, exec, s[6:7]
	s_waitcnt vmcnt(0)

; DEVI unsigned xb_ld(unsigned* p)              { return __hip_atomic_load(p, __ATOMIC_RELAXED, __HIP_MEMORY_SCOPE_AGENT); }
; DEVI unsigned xb_add(unsigned* p, unsigned v) { return __hip_atomic_fetch_add(p, v, __ATOMIC_RELAXED, __HIP_MEMORY_SCOPE_AGENT); }
; #define XB_SPIN(cond, bar) do { unsigned _sp = 0; while (cond) { __builtin_amdgcn_s_sleep(1); \
;     if ((++_sp & 255u) == 0u) { if (xb_ld(&(bar)[XB_TMO])) break; if (_sp > XB_SPIN_CAP) { atomicAdd(&(bar)[XB_TMO], 1u); break; } } } } while (0)
; DEVI void xcd_barrier(unsigned* bar, volatile LAS unsigned* st) {
;     ...
;             else XB_SPIN(xb_ld(&bar[XB_TOPGEN]) == tg, bar);
;             __builtin_amdgcn_fence(__ATOMIC_ACQUIRE, "agent");
;             xb_add(&bar[XB_XGEN(x)], 1u);
;             asm volatile("s_waitcnt vmcnt(0)" ::: "memory");
.LBB0_2611:
	s_or_b64 exec, exec, s[4:5]
	s_mov_b64 s[4:5], exec
	v_mbcnt_lo_u32_b32 v0, s4, 0
	v_mbcnt_hi_u32_b32 v0, s5, v0
	v_cmp_eq_u32_e32 vcc, 0, v0
	s_waitcnt vmcnt(0)
	buffer_inv sc1
	s_and_saveexec_b64 s[6:7], vcc
	s_cbranch_execz .LBB0_2613
	s_bcnt1_i32_b64 s4, s[4:5]
	v_mov_b32_e32 v0, 0x2000
	v_mov_b32_e32 v1, s4
.LBB0_2613:
	s_or_b64 exec, exec, s[6:7]
	s_waitcnt vmcnt(0)

; DEVI unsigned xb_ld(unsigned* p)              { return __hip_atomic_load(p, __ATOMIC_RELAXED, __HIP_MEMORY_SCOPE_AGENT); }
; DEVI unsigned xb_add(unsigned* p, unsigned v) { return __hip_atomic_fetch_add(p, v, __ATOMIC_RELAXED, __HIP_MEMORY_SCOPE_AGENT); }
; #define XB_SPIN(cond, bar) do { unsigned _sp = 0; while (cond) { __builtin_amdgcn_s_sleep(1); \
;     if ((++_sp & 255u) == 0u) { if (xb_ld(&(bar)[XB_TMO])) break; if (_sp > XB_SPIN_CAP) { atomicAdd(&(bar)[XB_TMO], 1u); break; } } } } while (0)
; DEVI void xcd_barrier(unsigned* bar, volatile LAS unsigned* st) {
;     ...
;             else XB_SPIN(xb_ld(&bar[XB_TOPGEN]) == tg, bar);
;             __builtin_amdgcn_fence(__ATOMIC_ACQUIRE, "agent");
;             xb_add(&bar[XB_XGEN(x)], 1u);
;             asm volatile("s_waitcnt vmcnt(0)" ::: "memory");
.LBB0_2705:
	s_or_b64 exec, exec, s[4:5]
	s_mov_b64 s[4:5], exec
	v_mbcnt_lo_u32_b32 v0, s4, 0
	v_mbcnt_hi_u32_b32 v0, s5, v0
	v_cmp_eq_u32_e32 vcc, 0, v0
	s_waitcnt vmcnt(0)
	buffer_inv sc1
	s_and_saveexec_b64 s[6:7], vcc
	s_cbranch_execz .LBB0_2707
	s_bcnt1_i32_b64 s4, s[4:5]
	v_mov_b32_e32 v0, 0x2000
	v_mov_b32_e32 v1, s4
.LBB0_2707:
	s_or_b64 exec, exec, s[6:7]
	s_waitcnt vmcnt(0)

; DEVI unsigned xb_ld(unsigned* p)              { return __hip_atomic_load(p, __ATOMIC_RELAXED, __HIP_MEMORY_SCOPE_AGENT); }
; DEVI unsigned xb_add(unsigned* p, unsigned v) { return __hip_atomic_fetch_add(p, v, __ATOMIC_RELAXED, __HIP_MEMORY_SCOPE_AGENT); }
; #define XB_SPIN(cond, bar) do { unsigned _sp = 0; while (cond) { __builtin_amdgcn_s_sleep(1); \
;     if ((++_sp & 255u) == 0u) { if (xb_ld(&(bar)[XB_TMO])) break; if (_sp > XB_SPIN_CAP) { atomicAdd(&(bar)[XB_TMO], 1u); break; } } } } while (0)
; DEVI void xcd_barrier(unsigned* bar, volatile LAS unsigned* st) {
;     ...
;             else XB_SPIN(xb_ld(&bar[XB_TOPGEN]) == tg, bar);
;             __builtin_amdgcn_fence(__ATOMIC_ACQUIRE, "agent");
;             xb_add(&bar[XB_XGEN(x)], 1u);
;             asm volatile("s_waitcnt vmcnt(0)" ::: "memory");
.LBB0_2799:
	s_or_b64 exec, exec, s[4:5]
	s_mov_b64 s[4:5], exec
	v_mbcnt_lo_u32_b32 v0, s4, 0
	v_mbcnt_hi_u32_b32 v0, s5, v0
	v_cmp_eq_u32_e32 vcc, 0, v0
	s_waitcnt vmcnt(0)
	buffer_inv sc1
	s_and_saveexec_b64 s[6:7], vcc
	s_cbranch_execz .LBB0_2801
	s_bcnt1_i32_b64 s4, s[4:5]
	v_mov_b32_e32 v0, 0x2000
	v_mov_b32_e32 v1, s4
.LBB0_2801:
	s_or_b64 exec, exec, s[6:7]
	s_waitcnt vmcnt(0)

; DEVI unsigned xb_ld(unsigned* p)              { return __hip_atomic_load(p, __ATOMIC_RELAXED, __HIP_MEMORY_SCOPE_AGENT); }
; DEVI unsigned xb_add(unsigned* p, unsigned v) { return __hip_atomic_fetch_add(p, v, __ATOMIC_RELAXED, __HIP_MEMORY_SCOPE_AGENT); }
; #define XB_SPIN(cond, bar) do { unsigned _sp = 0; while (cond) { __builtin_amdgcn_s_sleep(1); \
;     if ((++_sp & 255u) == 0u) { if (xb_ld(&(bar)[XB_TMO])) break; if (_sp > XB_SPIN_CAP) { atomicAdd(&(bar)[XB_TMO], 1u); break; } } } } while (0)
; DEVI void xcd_barrier(unsigned* bar, volatile LAS unsigned* st) {
;     ...
;             else XB_SPIN(xb_ld(&bar[XB_TOPGEN]) == tg, bar);
;             __builtin_amdgcn_fence(__ATOMIC_ACQUIRE, "agent");
;             xb_add(&bar[XB_XGEN(x)], 1u);
;             asm volatile("s_waitcnt vmcnt(0)" ::: "memory");
.LBB0_2914:
	s_or_b64 exec, exec, s[4:5]
	s_mov_b64 s[4:5], exec
	v_mbcnt_lo_u32_b32 v0, s4, 0
	v_mbcnt_hi_u32_b32 v0, s5, v0
	v_cmp_eq_u32_e32 vcc, 0, v0
	s_waitcnt vmcnt(0)
	buffer_inv sc1
	s_and_saveexec_b64 s[6:7], vcc
	s_cbranch_execz .LBB0_2916
	s_bcnt1_i32_b64 s4, s[4:5]
	v_mov_b32_e32 v0, 0x2000
	v_mov_b32_e32 v1, s4
.LBB0_2916:
	s_or_b64 exec, exec, s[6:7]
	s_waitcnt vmcnt(0)
